# adds removal of the serialized wait between the two K/V tile loads in the attention prologue
# baseline (speedup 1.0000x reference)
; __device__ __forceinline__ int v_st(int k, int c) { const int kk = (k & ~0xC) | ((k & 4) << 1) | ((k & 8) >> 1); return ((kk >> 3) * 4 + (c >> 5)) * 512 + ((kk & 7) * 32 + (c & 31)) * 2; }
; __device__ __forceinline__ int v_rd_base(int lane) { return ((lane & 3) << 3) | (((lane >> 2) & 3) << 6) | (((lane >> 4) & 1) << 5) | (((lane >> 5) & 1) << 8); }
; #define SLOAD(i, k0) do { sr_[i].vs0 = ld8(&Vh[(long)((k0) + sr) * LD + sc]); sr_[i].vs1 = ld8(&Vh[(long)((k0) + 32 + sr) * LD + sc]); \
;     sr_[i].ks0 = ld8(&Kh[(long)((k0) + sr) * LD + sc]); sr_[i].ks1 = ld8(&Kh[(long)((k0) + 32 + sr) * LD + sc]); } while (0)
; #define SWRITE(off, i) do { *(bf16x8*)((char*)V_lds + (off) + vst0) = sr_[i].vs0;          \
;     *(bf16x8*)((char*)V_lds + (off) + vst1) = sr_[i].vs1; int kc = sc * 2;               \
;     *(bf16x8*)((char*)K_lds + (off) + KSWZ(sr, kc)) = sr_[i].ks0;                       \
;     *(bf16x8*)((char*)K_lds + (off) + KSWZ(32 + sr, kc)) = sr_[i].ks1; } while (0)
; #define SWAIT() asm volatile("s_waitcnt vmcnt(0)" ::: "memory")
; __device__ __forceinline__ void attn_dense_body(const bf16_t* Qb, const bf16_t* __restrict__ Kh, const bf16_t* __restrict__ Vh, bf16_t* Ob, int seq, char* lds, const int wid,
;                                                 const float* __restrict__ qg, const float* __restrict__ rope, int t0) {
;     ...
;   const int sr = tid >> 4, sc = (tid & 15) * 8, vst0 = v_st(sr, sc), vst1 = v_st(32 + sr, sc);
;   const int vb0 = (int)(uintptr_t)V_lds + v_rd_base(lane);
;   struct { bf16x8 vs0, vs1, ks0, ks1; } sr_[1];
;     ...
;   f32x16 pA0, pA1, pB0, pB1; bf16x8 pa0, pa1, pa2, pa3; const int NT = seq / KVBLK;
;   if (wid >= 4) __builtin_amdgcn_s_setprio(1);
;   SLOAD(0, 0); SWAIT(); SWRITE(0, 0);
;   SLOAD(0, KVBLK); SWAIT(); SWRITE((int)SHM_V, 0); __syncthreads();
.LBB0_494:
	s_lshr_b32 s10, s21, 5
	s_and_b32 s12, s48, 0xfffff800
	s_and_b32 s10, s10, 3
	s_ashr_i32 s13, s12, 31
	s_lshl_b32 s42, s10, 8
	s_mul_hi_i32 s10, s9, 0x5800
	s_mulk_i32 s9, 0x5800
	s_add_u32 s9, s0, s9
	s_addc_u32 s10, s1, s10
	s_lshl_b32 s8, s8, 8
	v_readlane_b32 s4, v254, 31
	s_add_u32 s8, s9, s8
	s_addc_u32 s9, s10, 0
	v_add_u32_e32 v17, s4, v180
	v_ashrrev_i32_e32 v16, 4, v17
	s_add_u32 s10, s8, 0x1000
	v_lshlrev_b32_e32 v34, 3, v180
	v_add_u32_e32 v36, 32, v16
	s_addc_u32 s11, s9, 0
	v_and_b32_e32 v35, 0x78, v34
	v_mad_i64_i32 v[0:1], s[50:51], v16, s17, 0
	v_mad_i64_i32 v[2:3], s[50:51], v36, s17, 0
	v_add_u32_e32 v18, 64, v16
	v_add_u32_e32 v20, 0x60, v16
	s_add_u32 s8, s8, 0x1400
	v_or_b32_e32 v0, v0, v35
	v_or_b32_e32 v2, v2, v35
	v_mad_i64_i32 v[18:19], s[50:51], v18, s17, 0
	v_mad_i64_i32 v[20:21], s[50:51], v20, s17, 0
	s_addc_u32 s9, s9, 0
	v_lshlrev_b64 v[8:9], 1, v[0:1]
	v_lshlrev_b64 v[10:11], 1, v[2:3]
	v_or_b32_e32 v18, v18, v35
	v_or_b32_e32 v20, v20, v35
	v_lshl_add_u64 v[0:1], s[8:9], 0, v[8:9]
	v_lshl_add_u64 v[4:5], s[8:9], 0, v[10:11]
	v_lshl_add_u64 v[8:9], s[10:11], 0, v[8:9]
	v_lshl_add_u64 v[12:13], s[10:11], 0, v[10:11]
	v_lshlrev_b64 v[26:27], 1, v[18:19]
	v_lshlrev_b64 v[30:31], 1, v[20:21]
	global_load_dwordx4 v[0:3], v[0:1], off
	s_nop 0
	global_load_dwordx4 v[4:7], v[4:5], off
	s_nop 0
	global_load_dwordx4 v[8:11], v[8:9], off
	s_nop 0
	global_load_dwordx4 v[12:15], v[12:13], off
	s_nop 0
	v_lshl_add_u64 v[18:19], s[8:9], 0, v[26:27]
	v_lshl_add_u64 v[22:23], s[8:9], 0, v[30:31]
	global_load_dwordx4 v[18:21], v[18:19], off
	s_nop 0
	global_load_dwordx4 v[22:25], v[22:23], off
	v_lshl_add_u64 v[26:27], s[10:11], 0, v[26:27]
	global_load_dwordx4 v[26:29], v[26:27], off
	v_lshl_add_u64 v[30:31], s[10:11], 0, v[30:31]
	global_load_dwordx4 v[30:33], v[30:31], off
	v_and_b32_e32 v38, 0xfffff0, v16
	v_lshlrev_b32_e32 v39, 1, v16
	v_lshrrev_b32_e32 v40, 1, v16
	v_and_b32_e32 v41, 3, v16
	v_and_or_b32 v38, v39, 8, v38
	v_and_or_b32 v39, v40, 4, v41
	v_and_b32_e32 v41, 0xfffff0, v36
	v_lshlrev_b32_e32 v43, 1, v36
	v_bfe_u32 v37, v34, 5, 2
	v_and_b32_e32 v17, 0x70, v17
	v_lshlrev_b32_e32 v35, 1, v35
	v_lshlrev_b32_e32 v42, 8, v16
	v_lshlrev_b32_e32 v36, 8, v36
	v_lshrrev_b32_e32 v38, 1, v38
	v_and_or_b32 v41, v43, 8, v41
	v_and_b32_e32 v40, 48, v35
	v_bitop3_b32 v165, v35, v42, v17 bitop3:0xde
	v_bitop3_b32 v168, v36, v35, v17 bitop3:0xf6
	v_or_b32_e32 v17, v38, v37
	v_lshrrev_b32_e32 v35, 1, v41
	v_lshlrev_b32_e32 v39, 6, v39
	v_lshlrev_b32_e32 v17, 9, v17
	v_or_b32_e32 v35, v35, v37
	v_or3_b32 v170, v17, v39, v40
	v_lshlrev_b32_e32 v17, 9, v35
	v_or3_b32 v171, v17, v39, v40
	v_add_u32_e32 v17, 0, v170
	v_add_u32_e32 v42, 0, v165
	v_add_u32_e32 v36, 0, v168
	v_add_u32_e32 v35, 0, v171
	s_cmp_lg_u32 0, -1
	v_lshlrev_b32_e32 v155, 4, v181
	s_cselect_b32 s10, 0, 0
	s_add_i32 s8, 0, 0x10000
	v_lshlrev_b32_e32 v176, 8, v182
	v_lshlrev_b32_e32 v154, 4, v180
	v_mov_b32_e32 v179, 0
	s_mov_b32 s9, 0
	s_waitcnt vmcnt(7)
	ds_write_b128 v17, v[0:3]
	s_waitcnt vmcnt(6)
	ds_write_b128 v35, v[4:7]
	s_waitcnt vmcnt(5)
	ds_write_b128 v42, v[8:11] offset:49152
	s_waitcnt vmcnt(4)
	ds_write_b128 v36, v[12:15] offset:49152
	s_waitcnt vmcnt(0)
	s_waitcnt vmcnt(3)
	ds_write_b128 v17, v[18:21] offset:16384
	s_waitcnt vmcnt(2)
	ds_write_b128 v35, v[22:25] offset:16384
	v_lshlrev_b32_e32 v17, 4, v182
	v_bitop3_b32 v175, v17, v155, s84 bitop3:0x6c
	v_add_u32_e32 v0, s8, v165
	v_add_u32_e32 v177, v175, v176
	s_waitcnt vmcnt(1)
	ds_write_b128 v0, v[26:29]
	v_add_u32_e32 v0, s8, v168
	v_add_u32_e32 v4, 0, v177
	s_waitcnt vmcnt(0)
	ds_write_b128 v0, v[30:33]
	s_waitcnt lgkmcnt(0)
	s_barrier
; #define SLOAD(i, k0) do { sr_[i].vs0 = ld8(&Vh[(long)((k0) + sr) * LD + sc]); sr_[i].vs1 = ld8(&Vh[(long)((k0) + 32 + sr) * LD + sc]); \
;     sr_[i].ks0 = ld8(&Kh[(long)((k0) + sr) * LD + sc]); sr_[i].ks1 = ld8(&Kh[(long)((k0) + 32 + sr) * LD + sc]); } while (0)
; #define SWRITE(off, i) do { *(bf16x8*)((char*)V_lds + (off) + vst0) = sr_[i].vs0;          \
;     *(bf16x8*)((char*)V_lds + (off) + vst1) = sr_[i].vs1; int kc = sc * 2;               \
;     *(bf16x8*)((char*)K_lds + (off) + KSWZ(sr, kc)) = sr_[i].ks0;                       \
;     *(bf16x8*)((char*)K_lds + (off) + KSWZ(32 + sr, kc)) = sr_[i].ks1; } while (0)
; #define SWAIT() asm volatile("s_waitcnt vmcnt(0)" ::: "memory")
; __device__ __forceinline__ void qkt(f32x16& p0, f32x16& p1, const bf16_t* Ks, const bf16x8* qr, int r32, int hi) {
;   p0 = f32x16{}; p1 = f32x16{};
; #pragma unroll
;   for (int d0 = 0; d0 < 8; ++d0) { int cb = (d0 * 16 + hi * 8) * 2;
;     bf16x8 b0 = *reinterpret_cast<const bf16x8*>((const char*)Ks + KSWZ(r32, cb));
;     bf16x8 b1 = *reinterpret_cast<const bf16x8*>((const char*)Ks + KSWZ(32 + r32, cb));
;     p0 = __builtin_amdgcn_mfma_f32_32x32x16_bf16(b0, qr[d0], p0, 0, 0, 0);
;     p1 = __builtin_amdgcn_mfma_f32_32x32x16_bf16(b1, qr[d0], p1, 0, 0, 0); }
; }
; __device__ __forceinline__ void attn_dense_body(const bf16_t* Qb, const bf16_t* __restrict__ Kh, const bf16_t* __restrict__ Vh, bf16_t* Ob, int seq, char* lds, const int wid,
;                                                 const float* __restrict__ qg, const float* __restrict__ rope, int t0) {
;     ...
;   f32x16 pA0, pA1, pB0, pB1; bf16x8 pa0, pa1, pa2, pa3; const int NT = seq / KVBLK;
;   if (wid >= 4) __builtin_amdgcn_s_setprio(1);
;   SLOAD(0, 0); SWAIT(); SWRITE(0, 0);
;   SLOAD(0, KVBLK); SWAIT(); SWRITE((int)SHM_V, 0); __syncthreads();
;   qkt(pA0, pA1, K_lds, qr, r32, hi); expHalf(pA0);
;   int o0 = 0, o1 = (int)SHM_V, o2 = 2 * (int)SHM_V;
	ds_read_b128 v[0:3], v4 offset:49152
	ds_read_b128 v[18:21], v4 offset:57344
	s_waitcnt lgkmcnt(1)
	v_mfma_f32_32x32x16_bf16 v[0:15], v[0:3], v[140:143], 0
	v_mov_b32_e32 v27, v179
	v_mov_b32_e32 v28, v179
	v_mov_b32_e32 v29, v179
	v_mov_b32_e32 v30, v179
	v_mov_b32_e32 v31, v179
	v_mov_b32_e32 v32, 0
	v_mov_b32_e32 v33, v179
	s_waitcnt lgkmcnt(0)
	v_mfma_f32_32x32x16_bf16 v[64:79], v[18:21], v[140:143], 0
	v_add_u32_e32 v18, 32, v155
	v_bitop3_b32 v174, v18, v17, s84 bitop3:0x78
	v_add_u32_e32 v178, v174, v176
	v_add_u32_e32 v22, 0, v178
	ds_read_b128 v[18:21], v22 offset:49152
	ds_read_b128 v[22:25], v22 offset:57344
	v_mov_b32_e32 v35, v179
	v_mov_b32_e32 v36, v179
	s_waitcnt lgkmcnt(1)
	v_mfma_f32_32x32x16_bf16 v[0:15], v[18:21], v[136:139], v[0:15]
	v_add_u32_e32 v18, 64, v155
	v_bitop3_b32 v172, v18, v17, s84 bitop3:0x78
	v_add_u32_e32 v173, v172, v176
	v_mov_b32_e32 v37, v179
	v_mov_b32_e32 v38, v179
	v_mov_b32_e32 v39, v179
	v_mov_b32_e32 v40, v179
	s_waitcnt lgkmcnt(0)
	v_mfma_f32_32x32x16_bf16 v[64:79], v[22:25], v[136:139], v[64:79]
	v_add_u32_e32 v22, 0, v173
	ds_read_b128 v[18:21], v22 offset:49152
	ds_read_b128 v[22:25], v22 offset:57344
	v_mov_b32_e32 v41, v179
	v_mov_b32_e32 v42, v179
	v_mov_b32_e32 v43, v179
	v_mov_b32_e32 v44, v179
	v_mov_b32_e32 v45, v179
	s_waitcnt lgkmcnt(1)
	v_mfma_f32_32x32x16_bf16 v[0:15], v[18:21], v[132:135], v[0:15]
	v_add_u32_e32 v18, 0x60, v155
	v_bitop3_b32 v166, v18, v17, s84 bitop3:0x78
	v_add_u32_e32 v169, v166, v176
	v_mov_b32_e32 v46, v179
	v_mov_b32_e32 v47, v179
	v_mov_b32_e32 v48, 0
	v_mov_b32_e32 v49, v179
	s_waitcnt lgkmcnt(0)
	v_mfma_f32_32x32x16_bf16 v[64:79], v[22:25], v[132:135], v[64:79]
	v_add_u32_e32 v22, 0, v169
	ds_read_b128 v[18:21], v22 offset:49152
	ds_read_b128 v[22:25], v22 offset:57344
	v_mov_b32_e32 v50, v179
	v_mov_b32_e32 v51, v179
	v_mov_b32_e32 v52, v179
	v_mov_b32_e32 v53, v179
	v_mov_b32_e32 v54, v179
	s_waitcnt lgkmcnt(1)
	v_mfma_f32_32x32x16_bf16 v[0:15], v[18:21], v[128:131], v[0:15]
	v_add_u32_e32 v18, 0x80, v155
	v_bitop3_b32 v164, v18, v17, s84 bitop3:0x78
	v_add_u32_e32 v167, v164, v176
	v_mov_b32_e32 v55, v179
	v_mov_b32_e32 v56, v179
	v_mov_b32_e32 v57, v179
	v_mov_b32_e32 v58, v179
	s_waitcnt lgkmcnt(0)
	v_mfma_f32_32x32x16_bf16 v[64:79], v[22:25], v[128:131], v[64:79]
	v_add_u32_e32 v22, 0, v167
	ds_read_b128 v[18:21], v22 offset:49152
	ds_read_b128 v[22:25], v22 offset:57344
	v_mov_b32_e32 v59, v179
	v_mov_b32_e32 v60, v179
	v_mov_b32_e32 v61, v179
	v_mov_b32_e32 v62, v179
	v_mov_b32_e32 v63, v179
	s_waitcnt lgkmcnt(1)
	v_mfma_f32_32x32x16_bf16 v[0:15], v[18:21], v[124:127], v[0:15]
	v_add_u32_e32 v18, 0xa0, v155
	v_bitop3_b32 v161, v18, v17, s84 bitop3:0x78
	v_add_u32_e32 v163, v161, v176
	s_waitcnt lgkmcnt(0)
	v_mfma_f32_32x32x16_bf16 v[64:79], v[22:25], v[124:127], v[64:79]
	v_add_u32_e32 v22, 0, v163
	ds_read_b128 v[18:21], v22 offset:49152
	ds_read_b128 v[22:25], v22 offset:57344
	s_waitcnt lgkmcnt(1)
	v_mfma_f32_32x32x16_bf16 v[0:15], v[18:21], v[120:123], v[0:15]
	v_add_u32_e32 v18, 0xc0, v155
	v_bitop3_b32 v160, v18, v17, s84 bitop3:0x78
	v_add_u32_e32 v162, v160, v176
	s_waitcnt lgkmcnt(0)
	v_mfma_f32_32x32x16_bf16 v[64:79], v[22:25], v[120:123], v[64:79]
	v_add_u32_e32 v22, 0, v162
	ds_read_b128 v[18:21], v22 offset:49152
	ds_read_b128 v[22:25], v22 offset:57344
	s_waitcnt lgkmcnt(1)
	v_mfma_f32_32x32x16_bf16 v[0:15], v[18:21], v[116:119], v[0:15]
	v_add_u32_e32 v18, 0xe0, v155
	v_bitop3_b32 v158, v18, v17, s84 bitop3:0x78
	v_add_u32_e32 v159, v158, v176
	v_add_u32_e32 v17, 0, v159
	ds_read_b128 v[18:21], v17 offset:49152
	s_waitcnt lgkmcnt(1)
	v_mfma_f32_32x32x16_bf16 v[64:79], v[22:25], v[116:119], v[64:79]
	v_and_b32_e32 v22, 0xc0, v154
	v_and_or_b32 v26, v34, 24, v22
	ds_read_b128 v[22:25], v17 offset:57344
	v_lshlrev_b32_e32 v17, 1, v180
	v_and_b32_e32 v17, 32, v17
	s_waitcnt lgkmcnt(1)
	v_mfma_f32_32x32x16_bf16 v[0:15], v[18:21], v[112:115], v[0:15]
	v_and_b32_e32 v18, 0x100, v34
	v_or3_b32 v156, v26, v17, v18
	v_ashrrev_i32_e32 v17, 31, v16
	v_add_u32_e32 v157, s10, v156
	v_mov_b32_e32 v18, v179
	v_mov_b32_e32 v19, v179
	v_mov_b32_e32 v20, v179
	s_waitcnt lgkmcnt(0)
	v_mfma_f32_32x32x16_bf16 v[64:79], v[22:25], v[112:115], v[64:79]
	s_nop 2
	v_exp_f32_e32 v144, v0
	v_exp_f32_e32 v145, v1
	v_lshl_add_u64 v[0:1], v[16:17], 0, s[12:13]
	v_exp_f32_e32 v147, v2
	v_exp_f32_e32 v188, v3
	v_exp_f32_e32 v146, v4
	v_exp_f32_e32 v187, v5
	v_exp_f32_e32 v189, v6
	v_exp_f32_e32 v190, v7
	v_exp_f32_e32 v148, v8
	v_exp_f32_e32 v149, v9
	v_exp_f32_e32 v150, v10
	v_exp_f32_e32 v151, v11
	v_exp_f32_e32 v183, v12
	v_exp_f32_e32 v184, v13
	v_exp_f32_e32 v185, v14
	v_exp_f32_e32 v186, v15
	v_mad_u64_u32 v[2:3], s[10:11], v0, s16, 0
	v_and_b32_e32 v0, 15, v180
	v_lshlrev_b32_e32 v0, 4, v0
	v_mad_i32_i24 v1, v1, s16, v3
	v_or3_b32 v0, v2, s42, v0
	v_lshl_add_u64 v[152:153], s[44:45], 0, v[0:1]
	s_movk_i32 s11, 0x4000
	s_mov_b32 s13, 0x8000
	s_mov_b32 s10, -2
	v_mov_b32_e32 v0, 0
	v_mov_b32_e32 v1, v179
	v_mov_b32_e32 v2, v179
	v_mov_b32_e32 v3, v179
	v_mov_b32_e32 v4, v179
	v_mov_b32_e32 v5, v179
	v_mov_b32_e32 v6, v179
	v_mov_b32_e32 v7, v179
	v_mov_b32_e32 v8, v179
	v_mov_b32_e32 v9, v179
	v_mov_b32_e32 v10, v179
	v_mov_b32_e32 v11, v179
	v_mov_b32_e32 v12, v179
	v_mov_b32_e32 v13, v179
	v_mov_b32_e32 v14, v179
	v_mov_b32_e32 v15, v179
	v_mov_b32_e32 v16, 0
	v_mov_b32_e32 v17, v179
	v_mov_b32_e32 v21, v179
	v_mov_b32_e32 v22, v179
	v_mov_b32_e32 v23, v179
	v_mov_b32_e32 v24, v179
	v_mov_b32_e32 v25, v179
	v_mov_b32_e32 v26, v179
	v_mov_b32_e32 v34, v179
